# grid barrier inside the layer loop: waiting workgroups poll the top-level generation word directly (per-XCD generation hop removed)
# speedup vs baseline: 1.0208x; 1.0010x over previous
; DI unsigned xb_ld(unsigned* p)              { return __hip_atomic_load(p, __ATOMIC_RELAXED, __HIP_MEMORY_SCOPE_AGENT); }
; DI unsigned xb_add(unsigned* p, unsigned v) { return __hip_atomic_fetch_add(p, v, __ATOMIC_RELAXED, __HIP_MEMORY_SCOPE_AGENT); }
; #define XB_SPIN(cond, bar) do { unsigned _sp = 0; while (cond) { __builtin_amdgcn_s_sleep(1); \
;     if ((++_sp & 255u) == 0u) { if (xb_ld(&(bar)[XB_TMO])) break; if (_sp > XB_SPIN_CAP) { atomicAdd(&(bar)[XB_TMO], 1u); break; } } } } while (0)
; DI void xcd_barrier(const XcdBarrier& b) {
;     ...
;             const unsigned og = xb_add(&bar[XB_TOP], 1u);
;             const unsigned tg = og / nx;
;             if (og + 1u == (tg + 1u) * nx) xb_add(&bar[XB_TOPGEN], 1u);
;             else XB_SPIN(xb_ld(&bar[XB_TOPGEN]) == tg, bar);
;             __builtin_amdgcn_fence(__ATOMIC_ACQUIRE, "agent");
;             xb_add(&bar[XB_XGEN(b.x)], 1u);
;             asm volatile("s_waitcnt vmcnt(0)" ::: "memory");
.LBB0_171:
	s_or_b64 exec, exec, s[36:37]
	s_waitcnt vmcnt(0)
	buffer_inv sc1
	s_waitcnt vmcnt(0)

; DI unsigned xb_ld(unsigned* p)              { return __hip_atomic_load(p, __ATOMIC_RELAXED, __HIP_MEMORY_SCOPE_AGENT); }
; DI unsigned xb_add(unsigned* p, unsigned v) { return __hip_atomic_fetch_add(p, v, __ATOMIC_RELAXED, __HIP_MEMORY_SCOPE_AGENT); }
; #define XB_SPIN(cond, bar) do { unsigned _sp = 0; while (cond) { __builtin_amdgcn_s_sleep(1); \
;     if ((++_sp & 255u) == 0u) { if (xb_ld(&(bar)[XB_TMO])) break; if (_sp > XB_SPIN_CAP) { atomicAdd(&(bar)[XB_TMO], 1u); break; } } } } while (0)
; DI void xcd_barrier(const XcdBarrier& b) {
;     ...
;         const unsigned old = xb_add(&bar[XB_XSUB(b.x)], 1u);
;         const unsigned gen = old / nloc;
;         if (old + 1u == (gen + 1u) * nloc) {
;             __builtin_amdgcn_fence(__ATOMIC_RELEASE, "agent");
;             asm volatile("s_waitcnt vmcnt(0)" ::: "memory");
;             const unsigned og = xb_add(&bar[XB_TOP], 1u);
;             const unsigned tg = og / nx;
;             if (og + 1u == (tg + 1u) * nx) xb_add(&bar[XB_TOPGEN], 1u);
;             else XB_SPIN(xb_ld(&bar[XB_TOPGEN]) == tg, bar);
;             __builtin_amdgcn_fence(__ATOMIC_ACQUIRE, "agent");
;             xb_add(&bar[XB_XGEN(b.x)], 1u);
;             asm volatile("s_waitcnt vmcnt(0)" ::: "memory");
;         } else {
;             XB_SPIN(xb_ld(&bar[XB_XGEN(b.x)]) == gen, bar);
.LBB0_202:
	global_atomic_add v3, v[128:129], v168, off sc0
	v_cvt_f32_u32_e32 v1, v2
	v_sub_u32_e32 v4, 0, v2
	v_rcp_iflag_f32_e32 v1, v1
	s_nop 0
	v_mul_f32_e32 v1, 0x4f7ffffe, v1
	v_cvt_u32_f32_e32 v1, v1
	v_mul_lo_u32 v4, v4, v1
	v_mul_hi_u32 v4, v1, v4
	v_add_u32_e32 v1, v1, v4
	s_waitcnt vmcnt(0)
	v_mul_hi_u32 v1, v3, v1
	v_mul_lo_u32 v4, v1, v2
	v_sub_u32_e32 v4, v3, v4
	v_add_u32_e32 v5, 1, v1
	v_cmp_ge_u32_e32 vcc, v4, v2
	v_add_u32_e32 v3, 1, v3
	s_nop 0
	v_cndmask_b32_e32 v1, v1, v5, vcc
	v_sub_u32_e32 v5, v4, v2
	v_cndmask_b32_e32 v4, v4, v5, vcc
	v_add_u32_e32 v5, 1, v1
	v_cmp_ge_u32_e32 vcc, v4, v2
	s_nop 1
	v_cndmask_b32_e32 v1, v1, v5, vcc
	v_mul_lo_u32 v4, v2, v1
	v_add_u32_e32 v2, v4, v2
	v_cmp_ne_u32_e32 vcc, v3, v2
	s_and_saveexec_b64 s[2:3], vcc
	s_xor_b64 s[38:39], exec, s[2:3]
	s_cbranch_execz .LBB0_216
	s_waitcnt lgkmcnt(0)
	v_readlane_b32 s4, v254, 9
	v_readlane_b32 s5, v254, 10
	s_nop 4
	global_load_dword v0, v133, s[4:5] sc1
	s_waitcnt vmcnt(0)
	v_cmp_eq_u32_e32 vcc, v0, v1
	s_and_saveexec_b64 s[40:41], vcc
	s_cbranch_execz .LBB0_215
	s_mov_b32 s2, 1
	s_mov_b64 s[42:43], 0
	s_branch .LBB0_206

; DI unsigned xb_ld(unsigned* p)              { return __hip_atomic_load(p, __ATOMIC_RELAXED, __HIP_MEMORY_SCOPE_AGENT); }
; #define XB_SPIN(cond, bar) do { unsigned _sp = 0; while (cond) { __builtin_amdgcn_s_sleep(1); \
;     if ((++_sp & 255u) == 0u) { if (xb_ld(&(bar)[XB_TMO])) break; if (_sp > XB_SPIN_CAP) { atomicAdd(&(bar)[XB_TMO], 1u); break; } } } } while (0)
; DI void xcd_barrier(const XcdBarrier& b) {
;     ...
;             XB_SPIN(xb_ld(&bar[XB_XGEN(b.x)]) == gen, bar);
.LBB0_208:
	v_readlane_b32 s4, v254, 9
	v_readlane_b32 s5, v254, 10
	s_nop 4
	global_load_dword v0, v133, s[4:5] sc1
	s_add_i32 s2, s2, 1
	s_mov_b64 s[48:49], -1
	s_waitcnt vmcnt(0)
	v_cmp_ne_u32_e32 vcc, v0, v1
	s_orn2_b64 s[46:47], vcc, exec
	s_branch .LBB0_205

; DI unsigned xb_ld(unsigned* p)              { return __hip_atomic_load(p, __ATOMIC_RELAXED, __HIP_MEMORY_SCOPE_AGENT); }
; DI unsigned xb_add(unsigned* p, unsigned v) { return __hip_atomic_fetch_add(p, v, __ATOMIC_RELAXED, __HIP_MEMORY_SCOPE_AGENT); }
; #define XB_SPIN(cond, bar) do { unsigned _sp = 0; while (cond) { __builtin_amdgcn_s_sleep(1); \
;     if ((++_sp & 255u) == 0u) { if (xb_ld(&(bar)[XB_TMO])) break; if (_sp > XB_SPIN_CAP) { atomicAdd(&(bar)[XB_TMO], 1u); break; } } } } while (0)
; DI void xcd_barrier(const XcdBarrier& b) {
;     ...
;             const unsigned og = xb_add(&bar[XB_TOP], 1u);
;             const unsigned tg = og / nx;
;             if (og + 1u == (tg + 1u) * nx) xb_add(&bar[XB_TOPGEN], 1u);
;             else XB_SPIN(xb_ld(&bar[XB_TOPGEN]) == tg, bar);
;             __builtin_amdgcn_fence(__ATOMIC_ACQUIRE, "agent");
;             xb_add(&bar[XB_XGEN(b.x)], 1u);
;             asm volatile("s_waitcnt vmcnt(0)" ::: "memory");
.LBB0_231:
	s_or_b64 exec, exec, s[40:41]
	s_and_saveexec_b64 s[40:41], s[42:43]
	s_cbranch_execz .LBB0_233
	global_atomic_add v[0:1], v168, off
.LBB0_233:
	s_or_b64 exec, exec, s[40:41]
	s_waitcnt vmcnt(0)
	buffer_inv sc1
	s_waitcnt vmcnt(0)
.LBB0_234:
	s_or_b64 exec, exec, s[38:39]

; DI unsigned xb_ld(unsigned* p)              { return __hip_atomic_load(p, __ATOMIC_RELAXED, __HIP_MEMORY_SCOPE_AGENT); }
; DI unsigned xb_add(unsigned* p, unsigned v) { return __hip_atomic_fetch_add(p, v, __ATOMIC_RELAXED, __HIP_MEMORY_SCOPE_AGENT); }
; #define XB_SPIN(cond, bar) do { unsigned _sp = 0; while (cond) { __builtin_amdgcn_s_sleep(1); \
;     if ((++_sp & 255u) == 0u) { if (xb_ld(&(bar)[XB_TMO])) break; if (_sp > XB_SPIN_CAP) { atomicAdd(&(bar)[XB_TMO], 1u); break; } } } } while (0)
; DI void xcd_barrier(const XcdBarrier& b) {
;     ...
;         const unsigned old = xb_add(&bar[XB_XSUB(b.x)], 1u);
;         const unsigned gen = old / nloc;
;         if (old + 1u == (gen + 1u) * nloc) {
;             __builtin_amdgcn_fence(__ATOMIC_RELEASE, "agent");
;             asm volatile("s_waitcnt vmcnt(0)" ::: "memory");
;             const unsigned og = xb_add(&bar[XB_TOP], 1u);
;             const unsigned tg = og / nx;
;             if (og + 1u == (tg + 1u) * nx) xb_add(&bar[XB_TOPGEN], 1u);
;             else XB_SPIN(xb_ld(&bar[XB_TOPGEN]) == tg, bar);
;             __builtin_amdgcn_fence(__ATOMIC_ACQUIRE, "agent");
;             xb_add(&bar[XB_XGEN(b.x)], 1u);
;             asm volatile("s_waitcnt vmcnt(0)" ::: "memory");
;         } else {
;             XB_SPIN(xb_ld(&bar[XB_XGEN(b.x)]) == gen, bar);
.LBB0_349:
	global_atomic_add v3, v[128:129], v168, off sc0
	v_cvt_f32_u32_e32 v1, v2
	v_sub_u32_e32 v4, 0, v2
	v_rcp_iflag_f32_e32 v1, v1
	s_nop 0
	v_mul_f32_e32 v1, 0x4f7ffffe, v1
	v_cvt_u32_f32_e32 v1, v1
	v_mul_lo_u32 v4, v4, v1
	v_mul_hi_u32 v4, v1, v4
	v_add_u32_e32 v1, v1, v4
	s_waitcnt vmcnt(0)
	v_mul_hi_u32 v1, v3, v1
	v_mul_lo_u32 v4, v1, v2
	v_sub_u32_e32 v4, v3, v4
	v_add_u32_e32 v5, 1, v1
	v_cmp_ge_u32_e32 vcc, v4, v2
	v_add_u32_e32 v3, 1, v3
	s_nop 0
	v_cndmask_b32_e32 v1, v1, v5, vcc
	v_sub_u32_e32 v5, v4, v2
	v_cndmask_b32_e32 v4, v4, v5, vcc
	v_add_u32_e32 v5, 1, v1
	v_cmp_ge_u32_e32 vcc, v4, v2
	s_nop 1
	v_cndmask_b32_e32 v1, v1, v5, vcc
	v_mul_lo_u32 v4, v2, v1
	v_add_u32_e32 v2, v4, v2
	v_cmp_ne_u32_e32 vcc, v3, v2
	s_and_saveexec_b64 s[2:3], vcc
	s_xor_b64 s[36:37], exec, s[2:3]
	s_cbranch_execz .LBB0_363
	s_waitcnt lgkmcnt(0)
	v_readlane_b32 s4, v254, 9
	v_readlane_b32 s5, v254, 10
	s_nop 4
	global_load_dword v0, v133, s[4:5] sc1
	s_waitcnt vmcnt(0)
	v_cmp_eq_u32_e32 vcc, v0, v1
	s_and_saveexec_b64 s[38:39], vcc
	s_cbranch_execz .LBB0_362
	s_mov_b32 s2, 1
	s_mov_b64 s[40:41], 0
	s_branch .LBB0_353

; DI unsigned xb_ld(unsigned* p)              { return __hip_atomic_load(p, __ATOMIC_RELAXED, __HIP_MEMORY_SCOPE_AGENT); }
; #define XB_SPIN(cond, bar) do { unsigned _sp = 0; while (cond) { __builtin_amdgcn_s_sleep(1); \
;     if ((++_sp & 255u) == 0u) { if (xb_ld(&(bar)[XB_TMO])) break; if (_sp > XB_SPIN_CAP) { atomicAdd(&(bar)[XB_TMO], 1u); break; } } } } while (0)
; DI void xcd_barrier(const XcdBarrier& b) {
;     ...
;             XB_SPIN(xb_ld(&bar[XB_XGEN(b.x)]) == gen, bar);
.LBB0_355:
	v_readlane_b32 s4, v254, 9
	v_readlane_b32 s5, v254, 10
	s_nop 4
	global_load_dword v0, v133, s[4:5] sc1
	s_add_i32 s2, s2, 1
	s_mov_b64 s[46:47], -1
	s_waitcnt vmcnt(0)
	v_cmp_ne_u32_e32 vcc, v0, v1
	s_orn2_b64 s[44:45], vcc, exec
	s_branch .LBB0_352

; DI unsigned xb_ld(unsigned* p)              { return __hip_atomic_load(p, __ATOMIC_RELAXED, __HIP_MEMORY_SCOPE_AGENT); }
; DI unsigned xb_add(unsigned* p, unsigned v) { return __hip_atomic_fetch_add(p, v, __ATOMIC_RELAXED, __HIP_MEMORY_SCOPE_AGENT); }
; #define XB_SPIN(cond, bar) do { unsigned _sp = 0; while (cond) { __builtin_amdgcn_s_sleep(1); \
;     if ((++_sp & 255u) == 0u) { if (xb_ld(&(bar)[XB_TMO])) break; if (_sp > XB_SPIN_CAP) { atomicAdd(&(bar)[XB_TMO], 1u); break; } } } } while (0)
; DI void xcd_barrier(const XcdBarrier& b) {
;     ...
;             const unsigned og = xb_add(&bar[XB_TOP], 1u);
;             const unsigned tg = og / nx;
;             if (og + 1u == (tg + 1u) * nx) xb_add(&bar[XB_TOPGEN], 1u);
;             else XB_SPIN(xb_ld(&bar[XB_TOPGEN]) == tg, bar);
;             __builtin_amdgcn_fence(__ATOMIC_ACQUIRE, "agent");
;             xb_add(&bar[XB_XGEN(b.x)], 1u);
;             asm volatile("s_waitcnt vmcnt(0)" ::: "memory");
.LBB0_675:
	s_or_b64 exec, exec, s[38:39]
	s_and_saveexec_b64 s[38:39], s[40:41]
	s_cbranch_execz .LBB0_677
	global_atomic_add v[0:1], v168, off
.LBB0_677:
	s_or_b64 exec, exec, s[38:39]
	s_waitcnt vmcnt(0)
	buffer_inv sc1
	s_waitcnt vmcnt(0)
.LBB0_678:
	s_or_b64 exec, exec, s[36:37]

; DI unsigned xb_ld(unsigned* p)              { return __hip_atomic_load(p, __ATOMIC_RELAXED, __HIP_MEMORY_SCOPE_AGENT); }
; DI unsigned xb_add(unsigned* p, unsigned v) { return __hip_atomic_fetch_add(p, v, __ATOMIC_RELAXED, __HIP_MEMORY_SCOPE_AGENT); }
; #define XB_SPIN(cond, bar) do { unsigned _sp = 0; while (cond) { __builtin_amdgcn_s_sleep(1); \
;     if ((++_sp & 255u) == 0u) { if (xb_ld(&(bar)[XB_TMO])) break; if (_sp > XB_SPIN_CAP) { atomicAdd(&(bar)[XB_TMO], 1u); break; } } } } while (0)
; DI void xcd_barrier(const XcdBarrier& b) {
;     ...
;             const unsigned og = xb_add(&bar[XB_TOP], 1u);
;             const unsigned tg = og / nx;
;             if (og + 1u == (tg + 1u) * nx) xb_add(&bar[XB_TOPGEN], 1u);
;             else XB_SPIN(xb_ld(&bar[XB_TOPGEN]) == tg, bar);
;             __builtin_amdgcn_fence(__ATOMIC_ACQUIRE, "agent");
;             xb_add(&bar[XB_XGEN(b.x)], 1u);
;             asm volatile("s_waitcnt vmcnt(0)" ::: "memory");
.LBB0_795:
	s_or_b64 exec, exec, s[38:39]
	s_and_saveexec_b64 s[38:39], s[40:41]
	s_cbranch_execz .LBB0_797
	global_atomic_add v[0:1], v168, off
.LBB0_797:
	s_or_b64 exec, exec, s[38:39]
	s_waitcnt vmcnt(0)
	buffer_inv sc1
	s_waitcnt vmcnt(0)
.LBB0_798:
	s_or_b64 exec, exec, s[36:37]
